# sample-row attention P.V rewritten: batched V loads (16 in flight) + v_mfma_f32_16x16x4_f32 instead of one serialized load per key
# speedup vs baseline: 1.0398x; 1.0191x over previous
; __device__ __forceinline__ unsigned f2bf(float f) { unsigned u = __builtin_bit_cast(unsigned, f); return (u + 0x7fffu + ((u >> 16) & 1u)) >> 16; }
; template <int FOX> __device__ __forceinline__ void sample_unit(int s, int h, LAS unsigned char* lds, const KA& A) {
;     ...
; #pragma unroll
;       for (int i = 0; i < 16; ++i) red[(wave * 16 + i) * 64 + lane] = o[i];
;       __syncthreads();
; #pragma unroll
;       for (int rr = 0; rr < 2; ++rr) { const int i = wave * 2 + rr; float a = 0.f;
; #pragma unroll
;           for (int w = 0; w < 8; ++w) a += red[(w * 16 + i) * 64 + lane];
;           ((bf16*)(A.ws + WS_OB))[(size_t)(MP + s * 16 + i) * 1024 + h * 64 + lane] = (bf16)f2bf(a * linv[i]); } }
;     __syncthreads();
.Lsbd_tail:
	v_readlane_b32 s2, v255, 18
	v_lshl_add_u64 v[4:5], v[2:3], 1, s[4:5]
	s_lshl_b32 s28, s48, 1
	v_lshl_add_u32 v22, v2, 2, s2
	v_lshl_add_u32 v8, v43, 9, v22
	s_waitcnt lgkmcnt(0)
	s_barrier
	ds_read2st64_b32 v[0:1], v8 offset1:16
	ds_read2st64_b32 v[6:7], v8 offset0:32 offset1:48
	v_lshl_add_u64 v[4:5], v[4:5], 0, s[28:29]
	s_add_i32 s46, s46, s14
	s_cmpk_gt_i32 s46, 0xff
	s_waitcnt lgkmcnt(1)
	v_add_f32_e32 v0, 0, v0
	v_add_f32_e32 v0, v0, v1
	s_waitcnt lgkmcnt(0)
	v_add_f32_e32 v2, v0, v6
	ds_read2st64_b32 v[0:1], v8 offset0:64 offset1:80
	v_add_f32_e32 v2, v2, v7
	ds_read2st64_b32 v[6:7], v8 offset0:96 offset1:112
	v_lshl_add_u32 v8, v42, 2, 0
	ds_read_b64 v[8:9], v8 offset:8320
	s_waitcnt lgkmcnt(2)
	v_add_f32_e32 v0, v2, v0
	v_add_f32_e32 v0, v0, v1
	s_waitcnt lgkmcnt(1)
	v_add_f32_e32 v0, v0, v6
	v_add_f32_e32 v0, v0, v7
	s_waitcnt lgkmcnt(0)
	v_mul_f32_e32 v0, v0, v8
	v_bfe_u32 v1, v0, 16, 1
	v_add3_u32 v2, v0, v1, s74
	v_add_u32_e32 v0, s47, v42
	v_or_b32_e32 v8, 1, v42
	v_ashrrev_i32_e32 v1, 31, v0
	v_lshl_add_u32 v12, v8, 8, v22
	ds_read2st64_b32 v[6:7], v12 offset1:16
	v_lshlrev_b64 v[0:1], 11, v[0:1]
	v_lshl_add_u64 v[0:1], v[4:5], 0, v[0:1]
	global_store_short_d16_hi v[0:1], v2, off
	ds_read2st64_b32 v[0:1], v12 offset0:32 offset1:48
	ds_read2st64_b32 v[10:11], v12 offset0:64 offset1:80
	s_waitcnt lgkmcnt(2)
	v_add_f32_e32 v2, 0, v6
	v_add_f32_e32 v2, v2, v7
	ds_read2st64_b32 v[6:7], v12 offset0:96 offset1:112
	s_waitcnt lgkmcnt(2)
	v_add_f32_e32 v0, v2, v0
	v_add_f32_e32 v0, v0, v1
	s_waitcnt lgkmcnt(1)
	v_add_f32_e32 v0, v0, v10
	v_add_f32_e32 v0, v0, v11
	s_waitcnt lgkmcnt(0)
	v_add_f32_e32 v0, v0, v6
	v_add_f32_e32 v0, v0, v7
	v_mul_f32_e32 v0, v0, v9
	v_bfe_u32 v1, v0, 16, 1
	v_add3_u32 v2, v0, v1, s74
	v_add_u32_e32 v0, s47, v8
	v_ashrrev_i32_e32 v1, 31, v0
	v_lshlrev_b64 v[0:1], 11, v[0:1]
	v_lshl_add_u64 v[0:1], v[4:5], 0, v[0:1]
	global_store_short_d16_hi v[0:1], v2, off
	s_barrier
	s_cbranch_scc1 .LBB0_192

; #define LAS __attribute__((address_space(3)))
; template <int FOX> __device__ __forceinline__ void sample_unit(int s, int h, LAS unsigned char* lds, const KA& A) {
;     ...
;     {
;       LAS float* red = (LAS float*)(lds + 8448 + 16 * SP * 4);
;       float o[16];
; #pragma unroll
;       for (int i = 0; i < 16; ++i) o[i] = 0.f;
; #pragma unroll 8
;       for (int j = wave; j < NK; j += 8) { const float v = (j < NC) ? cv[((size_t)(s * NC + j) * 16 + h) * 64 + lane] : nv[(size_t)(s * 16 + j - NC) * 1024 + h * 64 + lane];
; #pragma unroll
;           for (int i = 0; i < 16; ++i) o[i] += S[i * SP + j] * v; }
.LBB0_183:
	s_waitcnt lgkmcnt(0)
	s_barrier
	s_mov_b64 exec, -1
	v_readfirstlane_b32 s28, v43
	v_and_b32_e32 v92, 15, v2
	v_bfe_u32 v93, v2, 4, 2
	v_mul_u32_u24_e32 v40, 0x1080, v92
	v_lshlrev_b32_e32 v92, 4, v92
	v_lshl_add_u32 v40, v93, 2, v40
	v_lshl_or_b32 v92, v93, 12, v92
	s_lshl_b32 s44, s28, 4
	s_nop 0
	v_add_u32_e32 v40, s44, v40
	v_add_u32_e32 v93, 0x2100, v40
	s_lshl_b32 s44, s48, 2
	s_lshl_b32 s45, s28, 2
	s_lshl_b32 s40, s26, 9
	s_add_i32 s40, s40, s45
	s_lshl_b32 s40, s40, 12
	s_add_i32 s40, s40, s44
	s_add_u32 s40, s42, s40
	s_addc_u32 s41, s43, 0
	s_add_i32 s45, s45, s2
	s_lshl_b32 s45, s45, 12
	s_add_i32 s45, s45, s44
	s_add_u32 s44, s6, s45
	s_addc_u32 s45, s7, 0
	s_cmp_lt_u32 s28, 4
	s_cselect_b32 s44, s44, s40
	s_cselect_b32 s45, s45, s41
	global_load_dwordx4 v[20:23], v92, s[40:41]
	s_add_u32 s40, s40, 0x20000
	s_addc_u32 s41, s41, 0
	global_load_dwordx4 v[24:27], v92, s[40:41]
	s_add_u32 s40, s40, 0x20000
	s_addc_u32 s41, s41, 0
	global_load_dwordx4 v[28:31], v92, s[40:41]
	s_add_u32 s40, s40, 0x20000
	s_addc_u32 s41, s41, 0
	global_load_dwordx4 v[32:35], v92, s[40:41]
	s_add_u32 s40, s40, 0x20000
	s_addc_u32 s41, s41, 0
	global_load_dwordx4 v[36:39], v92, s[40:41]
	s_add_u32 s40, s40, 0x20000
	s_addc_u32 s41, s41, 0
	global_load_dwordx4 v[44:47], v92, s[40:41]
	s_add_u32 s40, s40, 0x20000
	s_addc_u32 s41, s41, 0
	global_load_dwordx4 v[48:51], v92, s[40:41]
	s_add_u32 s40, s40, 0x20000
	s_addc_u32 s41, s41, 0
	global_load_dwordx4 v[56:59], v92, s[40:41]
	s_add_u32 s40, s40, 0x20000
	s_addc_u32 s41, s41, 0
	global_load_dwordx4 v[60:63], v92, s[40:41]
	s_add_u32 s40, s40, 0x20000
	s_addc_u32 s41, s41, 0
	global_load_dwordx4 v[64:67], v92, s[40:41]
	s_add_u32 s40, s40, 0x20000
	s_addc_u32 s41, s41, 0
	global_load_dwordx4 v[68:71], v92, s[40:41]
	s_add_u32 s40, s40, 0x20000
	s_addc_u32 s41, s41, 0
	global_load_dwordx4 v[72:75], v92, s[40:41]
	s_add_u32 s40, s40, 0x20000
	s_addc_u32 s41, s41, 0
	global_load_dwordx4 v[76:79], v92, s[40:41]
	s_add_u32 s40, s40, 0x20000
	s_addc_u32 s41, s41, 0
	global_load_dwordx4 v[80:83], v92, s[40:41]
	s_add_u32 s40, s40, 0x20000
	s_addc_u32 s41, s41, 0
	global_load_dwordx4 v[84:87], v92, s[40:41]
	s_add_u32 s40, s40, 0x20000
	s_addc_u32 s41, s41, 0
	global_load_dwordx4 v[88:91], v92, s[40:41]
	s_add_u32 s40, s40, 0x20000
	s_addc_u32 s41, s41, 0
	ds_read_b32 v40, v93 offset:0
	ds_read_b32 v41, v93 offset:128
	s_waitcnt vmcnt(15) lgkmcnt(1)
	v_mfma_f32_16x16x4_f32 v[4:7], v40, v20, 0
	v_mfma_f32_16x16x4_f32 v[8:11], v40, v21, 0
	v_mfma_f32_16x16x4_f32 v[12:15], v40, v22, 0
	v_mfma_f32_16x16x4_f32 v[16:19], v40, v23, 0
	ds_read_b32 v52, v93 offset:256
	s_waitcnt vmcnt(14) lgkmcnt(1)
	v_mfma_f32_16x16x4_f32 v[4:7], v41, v24, v[4:7]
	v_mfma_f32_16x16x4_f32 v[8:11], v41, v25, v[8:11]
	v_mfma_f32_16x16x4_f32 v[12:15], v41, v26, v[12:15]
	v_mfma_f32_16x16x4_f32 v[16:19], v41, v27, v[16:19]
	ds_read_b32 v53, v93 offset:384
	s_waitcnt vmcnt(13) lgkmcnt(1)
	v_mfma_f32_16x16x4_f32 v[4:7], v52, v28, v[4:7]
	v_mfma_f32_16x16x4_f32 v[8:11], v52, v29, v[8:11]
	v_mfma_f32_16x16x4_f32 v[12:15], v52, v30, v[12:15]
	v_mfma_f32_16x16x4_f32 v[16:19], v52, v31, v[16:19]
	ds_read_b32 v40, v93 offset:512
	s_waitcnt vmcnt(12) lgkmcnt(1)
	v_mfma_f32_16x16x4_f32 v[4:7], v53, v32, v[4:7]
	v_mfma_f32_16x16x4_f32 v[8:11], v53, v33, v[8:11]
	v_mfma_f32_16x16x4_f32 v[12:15], v53, v34, v[12:15]
	v_mfma_f32_16x16x4_f32 v[16:19], v53, v35, v[16:19]
	ds_read_b32 v41, v93 offset:640
	s_waitcnt vmcnt(11) lgkmcnt(1)
	v_mfma_f32_16x16x4_f32 v[4:7], v40, v36, v[4:7]
	v_mfma_f32_16x16x4_f32 v[8:11], v40, v37, v[8:11]
	v_mfma_f32_16x16x4_f32 v[12:15], v40, v38, v[12:15]
	v_mfma_f32_16x16x4_f32 v[16:19], v40, v39, v[16:19]
	ds_read_b32 v52, v93 offset:768
	s_waitcnt vmcnt(10) lgkmcnt(1)
	v_mfma_f32_16x16x4_f32 v[4:7], v41, v44, v[4:7]
	v_mfma_f32_16x16x4_f32 v[8:11], v41, v45, v[8:11]
	v_mfma_f32_16x16x4_f32 v[12:15], v41, v46, v[12:15]
	v_mfma_f32_16x16x4_f32 v[16:19], v41, v47, v[16:19]
	ds_read_b32 v53, v93 offset:896
	s_waitcnt vmcnt(9) lgkmcnt(1)
	v_mfma_f32_16x16x4_f32 v[4:7], v52, v48, v[4:7]
	v_mfma_f32_16x16x4_f32 v[8:11], v52, v49, v[8:11]
	v_mfma_f32_16x16x4_f32 v[12:15], v52, v50, v[12:15]
	v_mfma_f32_16x16x4_f32 v[16:19], v52, v51, v[16:19]
	ds_read_b32 v40, v93 offset:1024
	s_waitcnt vmcnt(8) lgkmcnt(1)
	v_mfma_f32_16x16x4_f32 v[4:7], v53, v56, v[4:7]
	v_mfma_f32_16x16x4_f32 v[8:11], v53, v57, v[8:11]
	v_mfma_f32_16x16x4_f32 v[12:15], v53, v58, v[12:15]
	v_mfma_f32_16x16x4_f32 v[16:19], v53, v59, v[16:19]
	global_load_dwordx4 v[20:23], v92, s[44:45]
	ds_read_b32 v41, v93 offset:1152
	s_waitcnt vmcnt(8) lgkmcnt(1)
	v_mfma_f32_16x16x4_f32 v[4:7], v40, v60, v[4:7]
	v_mfma_f32_16x16x4_f32 v[8:11], v40, v61, v[8:11]
	v_mfma_f32_16x16x4_f32 v[12:15], v40, v62, v[12:15]
	v_mfma_f32_16x16x4_f32 v[16:19], v40, v63, v[16:19]
	ds_read_b32 v52, v93 offset:1280
	s_waitcnt vmcnt(7) lgkmcnt(1)
	v_mfma_f32_16x16x4_f32 v[4:7], v41, v64, v[4:7]
	v_mfma_f32_16x16x4_f32 v[8:11], v41, v65, v[8:11]
	v_mfma_f32_16x16x4_f32 v[12:15], v41, v66, v[12:15]
	v_mfma_f32_16x16x4_f32 v[16:19], v41, v67, v[16:19]
	ds_read_b32 v53, v93 offset:1408
	s_waitcnt vmcnt(6) lgkmcnt(1)
	v_mfma_f32_16x16x4_f32 v[4:7], v52, v68, v[4:7]
	v_mfma_f32_16x16x4_f32 v[8:11], v52, v69, v[8:11]
	v_mfma_f32_16x16x4_f32 v[12:15], v52, v70, v[12:15]
	v_mfma_f32_16x16x4_f32 v[16:19], v52, v71, v[16:19]
	ds_read_b32 v40, v93 offset:1536
	s_waitcnt vmcnt(5) lgkmcnt(1)
	v_mfma_f32_16x16x4_f32 v[4:7], v53, v72, v[4:7]
	v_mfma_f32_16x16x4_f32 v[8:11], v53, v73, v[8:11]
	v_mfma_f32_16x16x4_f32 v[12:15], v53, v74, v[12:15]
	v_mfma_f32_16x16x4_f32 v[16:19], v53, v75, v[16:19]
	ds_read_b32 v41, v93 offset:1664
	s_waitcnt vmcnt(4) lgkmcnt(1)
	v_mfma_f32_16x16x4_f32 v[4:7], v40, v76, v[4:7]
	v_mfma_f32_16x16x4_f32 v[8:11], v40, v77, v[8:11]
	v_mfma_f32_16x16x4_f32 v[12:15], v40, v78, v[12:15]
	v_mfma_f32_16x16x4_f32 v[16:19], v40, v79, v[16:19]
	ds_read_b32 v52, v93 offset:1792
	s_waitcnt vmcnt(3) lgkmcnt(1)
	v_mfma_f32_16x16x4_f32 v[4:7], v41, v80, v[4:7]
	v_mfma_f32_16x16x4_f32 v[8:11], v41, v81, v[8:11]
	v_mfma_f32_16x16x4_f32 v[12:15], v41, v82, v[12:15]
	v_mfma_f32_16x16x4_f32 v[16:19], v41, v83, v[16:19]
	ds_read_b32 v53, v93 offset:1920
	s_waitcnt vmcnt(2) lgkmcnt(1)
	v_mfma_f32_16x16x4_f32 v[4:7], v52, v84, v[4:7]
	v_mfma_f32_16x16x4_f32 v[8:11], v52, v85, v[8:11]
	v_mfma_f32_16x16x4_f32 v[12:15], v52, v86, v[12:15]
	v_mfma_f32_16x16x4_f32 v[16:19], v52, v87, v[16:19]
	ds_read_b32 v40, v93 offset:2048
	s_waitcnt vmcnt(1) lgkmcnt(1)
	v_mfma_f32_16x16x4_f32 v[4:7], v53, v88, v[4:7]
	v_mfma_f32_16x16x4_f32 v[8:11], v53, v89, v[8:11]
	v_mfma_f32_16x16x4_f32 v[12:15], v53, v90, v[12:15]
	v_mfma_f32_16x16x4_f32 v[16:19], v53, v91, v[16:19]
	s_cmp_lt_u32 s28, 4
	s_cbranch_scc0 .Lsbd_nonew
	s_waitcnt vmcnt(0) lgkmcnt(0)
	v_mfma_f32_16x16x4_f32 v[4:7], v40, v20, v[4:7]
	v_mfma_f32_16x16x4_f32 v[8:11], v40, v21, v[8:11]
	v_mfma_f32_16x16x4_f32 v[12:15], v40, v22, v[12:15]
	v_mfma_f32_16x16x4_f32 v[16:19], v40, v23, v[16:19]
; template <int FOX> __device__ __forceinline__ void sample_unit(int s, int h, LAS unsigned char* lds, const KA& A) {
;     ...
; #pragma unroll
;       for (int i = 0; i < 16; ++i) red[(wave * 16 + i) * 64 + lane] = o[i];
.Lsbd_nonew:
	s_waitcnt vmcnt(0) lgkmcnt(0)
	v_readlane_b32 s22, v255, 18
	v_and_b32_e32 v40, 15, v2
	v_bfe_u32 v41, v2, 4, 2
	v_lshlrev_b32_e32 v40, 4, v40
	s_lshl_b32 s26, s28, 12
	v_lshl_or_b32 v40, v41, 10, v40
	s_add_i32 s26, s26, s22
	s_nop 7
	v_add_u32_e32 v40, s26, v40
	ds_write2_b32 v40, v4, v8 offset0:0 offset1:1
	ds_write2_b32 v40, v12, v16 offset0:2 offset1:3
	ds_write2_b32 v40, v5, v9 offset0:64 offset1:65
	ds_write2_b32 v40, v13, v17 offset0:66 offset1:67
	ds_write2_b32 v40, v6, v10 offset0:128 offset1:129
	ds_write2_b32 v40, v14, v18 offset0:130 offset1:131
	ds_write2_b32 v40, v7, v11 offset0:192 offset1:193
	ds_write2_b32 v40, v15, v19 offset0:194 offset1:195
	s_branch .Lsbd_tail

; #define LAS __attribute__((address_space(3)))
; template <int FOX> __device__ __forceinline__ void sample_unit(int s, int h, LAS unsigned char* lds, const KA& A) {
;     ...
;     {
;       LAS float* red = (LAS float*)(lds + 8448 + 16 * SP * 4);
;       float o[16];
; #pragma unroll
;       for (int i = 0; i < 16; ++i) o[i] = 0.f;
; #pragma unroll 8
;       for (int j = wave; j < NK; j += 8) { const float v = (j < NC) ? cv[((size_t)(s * NC + j) * 16 + h) * 64 + lane] : nv[(size_t)(s * 16 + j - NC) * 1024 + h * 64 + lane];
; #pragma unroll
;           for (int i = 0; i < 16; ++i) o[i] += S[i * SP + j] * v; }
.LBB0_233:
	s_waitcnt lgkmcnt(0)
	s_barrier
	s_mov_b64 exec, -1
	v_readfirstlane_b32 s22, v55
	v_and_b32_e32 v92, 15, v0
	v_bfe_u32 v93, v0, 4, 2
	v_readlane_b32 s6, v255, 55
	v_readlane_b32 s7, v255, 56
	v_mul_u32_u24_e32 v40, 0x1080, v92
	v_lshlrev_b32_e32 v92, 4, v92
	v_lshl_add_u32 v40, v93, 2, v40
	v_lshl_or_b32 v92, v93, 12, v92
	s_lshl_b32 s28, s22, 4
	v_mov_b32_e32 v1, v3
	v_add_u32_e32 v40, s28, v40
	v_add_u32_e32 v93, 0x2100, v40
	s_lshl_b32 s42, s27, 2
	s_lshl_b32 s43, s22, 2
	s_lshl_b32 s28, s2, 10
	s_add_i32 s28, s28, s43
	s_lshl_b32 s28, s28, 12
	s_add_i32 s28, s28, s42
	s_add_u32 s46, s58, s28
	s_addc_u32 s47, s59, 0
	s_add_i32 s43, s43, s19
	s_lshl_b32 s43, s43, 12
	s_add_i32 s43, s43, s42
	s_add_u32 s48, s6, s43
	s_addc_u32 s49, s7, 0
	s_cmp_lt_u32 s22, 4
	s_cselect_b32 s48, s48, s46
	s_cselect_b32 s49, s49, s47
	global_load_dwordx4 v[20:23], v92, s[46:47]
	s_add_u32 s46, s46, 0x20000
	s_addc_u32 s47, s47, 0
	global_load_dwordx4 v[24:27], v92, s[46:47]
	s_add_u32 s46, s46, 0x20000
	s_addc_u32 s47, s47, 0
	global_load_dwordx4 v[28:31], v92, s[46:47]
	s_add_u32 s46, s46, 0x20000
	s_addc_u32 s47, s47, 0
	global_load_dwordx4 v[32:35], v92, s[46:47]
	s_add_u32 s46, s46, 0x20000
	s_addc_u32 s47, s47, 0
	global_load_dwordx4 v[36:39], v92, s[46:47]
	s_add_u32 s46, s46, 0x20000
	s_addc_u32 s47, s47, 0
	global_load_dwordx4 v[44:47], v92, s[46:47]
	s_add_u32 s46, s46, 0x20000
	s_addc_u32 s47, s47, 0
	global_load_dwordx4 v[48:51], v92, s[46:47]
	s_add_u32 s46, s46, 0x20000
	s_addc_u32 s47, s47, 0
	global_load_dwordx4 v[56:59], v92, s[46:47]
	s_add_u32 s46, s46, 0x20000
	s_addc_u32 s47, s47, 0
	global_load_dwordx4 v[60:63], v92, s[46:47]
	s_add_u32 s46, s46, 0x20000
	s_addc_u32 s47, s47, 0
	global_load_dwordx4 v[64:67], v92, s[46:47]
	s_add_u32 s46, s46, 0x20000
	s_addc_u32 s47, s47, 0
	global_load_dwordx4 v[68:71], v92, s[46:47]
	s_add_u32 s46, s46, 0x20000
	s_addc_u32 s47, s47, 0
	global_load_dwordx4 v[72:75], v92, s[46:47]
	s_add_u32 s46, s46, 0x20000
	s_addc_u32 s47, s47, 0
	global_load_dwordx4 v[76:79], v92, s[46:47]
	s_add_u32 s46, s46, 0x20000
	s_addc_u32 s47, s47, 0
	global_load_dwordx4 v[80:83], v92, s[46:47]
	s_add_u32 s46, s46, 0x20000
	s_addc_u32 s47, s47, 0
	global_load_dwordx4 v[84:87], v92, s[46:47]
	s_add_u32 s46, s46, 0x20000
	s_addc_u32 s47, s47, 0
	global_load_dwordx4 v[88:91], v92, s[46:47]
	s_add_u32 s46, s46, 0x20000
	s_addc_u32 s47, s47, 0
	ds_read_b32 v40, v93 offset:0
	ds_read_b32 v41, v93 offset:128
	s_waitcnt vmcnt(15) lgkmcnt(1)
	v_mfma_f32_16x16x4_f32 v[4:7], v40, v20, 0
	v_mfma_f32_16x16x4_f32 v[8:11], v40, v21, 0
	v_mfma_f32_16x16x4_f32 v[12:15], v40, v22, 0
	v_mfma_f32_16x16x4_f32 v[16:19], v40, v23, 0
	ds_read_b32 v52, v93 offset:256
	s_waitcnt vmcnt(14) lgkmcnt(1)
	v_mfma_f32_16x16x4_f32 v[4:7], v41, v24, v[4:7]
	v_mfma_f32_16x16x4_f32 v[8:11], v41, v25, v[8:11]
	v_mfma_f32_16x16x4_f32 v[12:15], v41, v26, v[12:15]
	v_mfma_f32_16x16x4_f32 v[16:19], v41, v27, v[16:19]
	ds_read_b32 v53, v93 offset:384
	s_waitcnt vmcnt(13) lgkmcnt(1)
	v_mfma_f32_16x16x4_f32 v[4:7], v52, v28, v[4:7]
	v_mfma_f32_16x16x4_f32 v[8:11], v52, v29, v[8:11]
	v_mfma_f32_16x16x4_f32 v[12:15], v52, v30, v[12:15]
	v_mfma_f32_16x16x4_f32 v[16:19], v52, v31, v[16:19]
	ds_read_b32 v40, v93 offset:512
	s_waitcnt vmcnt(12) lgkmcnt(1)
	v_mfma_f32_16x16x4_f32 v[4:7], v53, v32, v[4:7]
	v_mfma_f32_16x16x4_f32 v[8:11], v53, v33, v[8:11]
	v_mfma_f32_16x16x4_f32 v[12:15], v53, v34, v[12:15]
	v_mfma_f32_16x16x4_f32 v[16:19], v53, v35, v[16:19]
	ds_read_b32 v41, v93 offset:640
	s_waitcnt vmcnt(11) lgkmcnt(1)
	v_mfma_f32_16x16x4_f32 v[4:7], v40, v36, v[4:7]
	v_mfma_f32_16x16x4_f32 v[8:11], v40, v37, v[8:11]
	v_mfma_f32_16x16x4_f32 v[12:15], v40, v38, v[12:15]
	v_mfma_f32_16x16x4_f32 v[16:19], v40, v39, v[16:19]
	ds_read_b32 v52, v93 offset:768
	s_waitcnt vmcnt(10) lgkmcnt(1)
	v_mfma_f32_16x16x4_f32 v[4:7], v41, v44, v[4:7]
	v_mfma_f32_16x16x4_f32 v[8:11], v41, v45, v[8:11]
	v_mfma_f32_16x16x4_f32 v[12:15], v41, v46, v[12:15]
	v_mfma_f32_16x16x4_f32 v[16:19], v41, v47, v[16:19]
	ds_read_b32 v53, v93 offset:896
	s_waitcnt vmcnt(9) lgkmcnt(1)
	v_mfma_f32_16x16x4_f32 v[4:7], v52, v48, v[4:7]
	v_mfma_f32_16x16x4_f32 v[8:11], v52, v49, v[8:11]
	v_mfma_f32_16x16x4_f32 v[12:15], v52, v50, v[12:15]
	v_mfma_f32_16x16x4_f32 v[16:19], v52, v51, v[16:19]
	ds_read_b32 v40, v93 offset:1024
	s_waitcnt vmcnt(8) lgkmcnt(1)
	v_mfma_f32_16x16x4_f32 v[4:7], v53, v56, v[4:7]
	v_mfma_f32_16x16x4_f32 v[8:11], v53, v57, v[8:11]
	v_mfma_f32_16x16x4_f32 v[12:15], v53, v58, v[12:15]
	v_mfma_f32_16x16x4_f32 v[16:19], v53, v59, v[16:19]
	global_load_dwordx4 v[20:23], v92, s[46:47]
	s_add_u32 s46, s46, 0x20000
	s_addc_u32 s47, s47, 0
	global_load_dwordx4 v[24:27], v92, s[46:47]
	s_add_u32 s46, s46, 0x20000
	s_addc_u32 s47, s47, 0
	global_load_dwordx4 v[28:31], v92, s[46:47]
	s_add_u32 s46, s46, 0x20000
	s_addc_u32 s47, s47, 0
	global_load_dwordx4 v[32:35], v92, s[46:47]
	s_add_u32 s46, s46, 0x20000
	s_addc_u32 s47, s47, 0
	global_load_dwordx4 v[36:39], v92, s[46:47]
	s_add_u32 s46, s46, 0x20000
	s_addc_u32 s47, s47, 0
	global_load_dwordx4 v[44:47], v92, s[46:47]
	s_add_u32 s46, s46, 0x20000
	s_addc_u32 s47, s47, 0
	global_load_dwordx4 v[48:51], v92, s[46:47]
	s_add_u32 s46, s46, 0x20000
	s_addc_u32 s47, s47, 0
	global_load_dwordx4 v[56:59], v92, s[46:47]
	s_add_u32 s46, s46, 0x20000
	s_addc_u32 s47, s47, 0
	ds_read_b32 v41, v93 offset:1152
	s_waitcnt vmcnt(15) lgkmcnt(1)
	v_mfma_f32_16x16x4_f32 v[4:7], v40, v60, v[4:7]
	v_mfma_f32_16x16x4_f32 v[8:11], v40, v61, v[8:11]
	v_mfma_f32_16x16x4_f32 v[12:15], v40, v62, v[12:15]
	v_mfma_f32_16x16x4_f32 v[16:19], v40, v63, v[16:19]
	ds_read_b32 v52, v93 offset:1280
	s_waitcnt vmcnt(14) lgkmcnt(1)
; template <int FOX> __device__ __forceinline__ void sample_unit(int s, int h, LAS unsigned char* lds, const KA& A) {
;     ...
; #pragma unroll 8
;       for (int j = wave; j < NK; j += 8) { const float v = (j < NC) ? cv[((size_t)(s * NC + j) * 16 + h) * 64 + lane] : nv[(size_t)(s * 16 + j - NC) * 1024 + h * 64 + lane];
; #pragma unroll
;           for (int i = 0; i < 16; ++i) o[i] += S[i * SP + j] * v; }
	v_mfma_f32_16x16x4_f32 v[4:7], v41, v64, v[4:7]
	v_mfma_f32_16x16x4_f32 v[8:11], v41, v65, v[8:11]
	v_mfma_f32_16x16x4_f32 v[12:15], v41, v66, v[12:15]
	v_mfma_f32_16x16x4_f32 v[16:19], v41, v67, v[16:19]
	ds_read_b32 v53, v93 offset:1408
	s_waitcnt vmcnt(13) lgkmcnt(1)
	v_mfma_f32_16x16x4_f32 v[4:7], v52, v68, v[4:7]
	v_mfma_f32_16x16x4_f32 v[8:11], v52, v69, v[8:11]
	v_mfma_f32_16x16x4_f32 v[12:15], v52, v70, v[12:15]
	v_mfma_f32_16x16x4_f32 v[16:19], v52, v71, v[16:19]
	ds_read_b32 v40, v93 offset:1536
	s_waitcnt vmcnt(12) lgkmcnt(1)
	v_mfma_f32_16x16x4_f32 v[4:7], v53, v72, v[4:7]
	v_mfma_f32_16x16x4_f32 v[8:11], v53, v73, v[8:11]
	v_mfma_f32_16x16x4_f32 v[12:15], v53, v74, v[12:15]
	v_mfma_f32_16x16x4_f32 v[16:19], v53, v75, v[16:19]
	ds_read_b32 v41, v93 offset:1664
	s_waitcnt vmcnt(11) lgkmcnt(1)
	v_mfma_f32_16x16x4_f32 v[4:7], v40, v76, v[4:7]
	v_mfma_f32_16x16x4_f32 v[8:11], v40, v77, v[8:11]
	v_mfma_f32_16x16x4_f32 v[12:15], v40, v78, v[12:15]
	v_mfma_f32_16x16x4_f32 v[16:19], v40, v79, v[16:19]
	ds_read_b32 v52, v93 offset:1792
	s_waitcnt vmcnt(10) lgkmcnt(1)
	v_mfma_f32_16x16x4_f32 v[4:7], v41, v80, v[4:7]
	v_mfma_f32_16x16x4_f32 v[8:11], v41, v81, v[8:11]
	v_mfma_f32_16x16x4_f32 v[12:15], v41, v82, v[12:15]
	v_mfma_f32_16x16x4_f32 v[16:19], v41, v83, v[16:19]
	ds_read_b32 v53, v93 offset:1920
	s_waitcnt vmcnt(9) lgkmcnt(1)
	v_mfma_f32_16x16x4_f32 v[4:7], v52, v84, v[4:7]
	v_mfma_f32_16x16x4_f32 v[8:11], v52, v85, v[8:11]
	v_mfma_f32_16x16x4_f32 v[12:15], v52, v86, v[12:15]
	v_mfma_f32_16x16x4_f32 v[16:19], v52, v87, v[16:19]
	ds_read_b32 v40, v93 offset:2048
	s_waitcnt vmcnt(8) lgkmcnt(1)
	v_mfma_f32_16x16x4_f32 v[4:7], v53, v88, v[4:7]
	v_mfma_f32_16x16x4_f32 v[8:11], v53, v89, v[8:11]
	v_mfma_f32_16x16x4_f32 v[12:15], v53, v90, v[12:15]
	v_mfma_f32_16x16x4_f32 v[16:19], v53, v91, v[16:19]
	global_load_dwordx4 v[60:63], v92, s[46:47]
	s_add_u32 s46, s46, 0x20000
	s_addc_u32 s47, s47, 0
	global_load_dwordx4 v[64:67], v92, s[46:47]
	s_add_u32 s46, s46, 0x20000
	s_addc_u32 s47, s47, 0
	global_load_dwordx4 v[68:71], v92, s[46:47]
	s_add_u32 s46, s46, 0x20000
	s_addc_u32 s47, s47, 0
	global_load_dwordx4 v[72:75], v92, s[46:47]
	s_add_u32 s46, s46, 0x20000
	s_addc_u32 s47, s47, 0
	global_load_dwordx4 v[76:79], v92, s[46:47]
	s_add_u32 s46, s46, 0x20000
	s_addc_u32 s47, s47, 0
	global_load_dwordx4 v[80:83], v92, s[46:47]
	s_add_u32 s46, s46, 0x20000
	s_addc_u32 s47, s47, 0
	global_load_dwordx4 v[84:87], v92, s[46:47]
	s_add_u32 s46, s46, 0x20000
	s_addc_u32 s47, s47, 0
	global_load_dwordx4 v[88:91], v92, s[46:47]
	s_add_u32 s46, s46, 0x20000
	s_addc_u32 s47, s47, 0
	ds_read_b32 v41, v93 offset:2176
	s_waitcnt vmcnt(15) lgkmcnt(1)
	v_mfma_f32_16x16x4_f32 v[4:7], v40, v20, v[4:7]
	v_mfma_f32_16x16x4_f32 v[8:11], v40, v21, v[8:11]
	v_mfma_f32_16x16x4_f32 v[12:15], v40, v22, v[12:15]
	v_mfma_f32_16x16x4_f32 v[16:19], v40, v23, v[16:19]
	ds_read_b32 v52, v93 offset:2304
	s_waitcnt vmcnt(14) lgkmcnt(1)
	v_mfma_f32_16x16x4_f32 v[4:7], v41, v24, v[4:7]
	v_mfma_f32_16x16x4_f32 v[8:11], v41, v25, v[8:11]
	v_mfma_f32_16x16x4_f32 v[12:15], v41, v26, v[12:15]
	v_mfma_f32_16x16x4_f32 v[16:19], v41, v27, v[16:19]
	ds_read_b32 v53, v93 offset:2432
	s_waitcnt vmcnt(13) lgkmcnt(1)
	v_mfma_f32_16x16x4_f32 v[4:7], v52, v28, v[4:7]
	v_mfma_f32_16x16x4_f32 v[8:11], v52, v29, v[8:11]
	v_mfma_f32_16x16x4_f32 v[12:15], v52, v30, v[12:15]
	v_mfma_f32_16x16x4_f32 v[16:19], v52, v31, v[16:19]
	ds_read_b32 v40, v93 offset:2560
	s_waitcnt vmcnt(12) lgkmcnt(1)
	v_mfma_f32_16x16x4_f32 v[4:7], v53, v32, v[4:7]
	v_mfma_f32_16x16x4_f32 v[8:11], v53, v33, v[8:11]
	v_mfma_f32_16x16x4_f32 v[12:15], v53, v34, v[12:15]
	v_mfma_f32_16x16x4_f32 v[16:19], v53, v35, v[16:19]
	ds_read_b32 v41, v93 offset:2688
	s_waitcnt vmcnt(11) lgkmcnt(1)
	v_mfma_f32_16x16x4_f32 v[4:7], v40, v36, v[4:7]
	v_mfma_f32_16x16x4_f32 v[8:11], v40, v37, v[8:11]
	v_mfma_f32_16x16x4_f32 v[12:15], v40, v38, v[12:15]
	v_mfma_f32_16x16x4_f32 v[16:19], v40, v39, v[16:19]
	ds_read_b32 v52, v93 offset:2816
	s_waitcnt vmcnt(10) lgkmcnt(1)
	v_mfma_f32_16x16x4_f32 v[4:7], v41, v44, v[4:7]
	v_mfma_f32_16x16x4_f32 v[8:11], v41, v45, v[8:11]
	v_mfma_f32_16x16x4_f32 v[12:15], v41, v46, v[12:15]
	v_mfma_f32_16x16x4_f32 v[16:19], v41, v47, v[16:19]
	ds_read_b32 v53, v93 offset:2944
	s_waitcnt vmcnt(9) lgkmcnt(1)
	v_mfma_f32_16x16x4_f32 v[4:7], v52, v48, v[4:7]
	v_mfma_f32_16x16x4_f32 v[8:11], v52, v49, v[8:11]
	v_mfma_f32_16x16x4_f32 v[12:15], v52, v50, v[12:15]
	v_mfma_f32_16x16x4_f32 v[16:19], v52, v51, v[16:19]
	ds_read_b32 v40, v93 offset:3072
	s_waitcnt vmcnt(8) lgkmcnt(1)
	v_mfma_f32_16x16x4_f32 v[4:7], v53, v56, v[4:7]
	v_mfma_f32_16x16x4_f32 v[8:11], v53, v57, v[8:11]
	v_mfma_f32_16x16x4_f32 v[12:15], v53, v58, v[12:15]
	v_mfma_f32_16x16x4_f32 v[16:19], v53, v59, v[16:19]
	global_load_dwordx4 v[20:23], v92, s[48:49]
	ds_read_b32 v41, v93 offset:3200
	s_waitcnt vmcnt(8) lgkmcnt(1)
; __device__ __forceinline__ unsigned f2bf(float f) { unsigned u = __builtin_bit_cast(unsigned, f); return (u + 0x7fffu + ((u >> 16) & 1u)) >> 16; }
; template <int FOX> __device__ __forceinline__ void sample_unit(int s, int h, LAS unsigned char* lds, const KA& A) {
;     ...
; #pragma unroll 8
;       for (int j = wave; j < NK; j += 8) { const float v = (j < NC) ? cv[((size_t)(s * NC + j) * 16 + h) * 64 + lane] : nv[(size_t)(s * 16 + j - NC) * 1024 + h * 64 + lane];
; #pragma unroll
;           for (int i = 0; i < 16; ++i) o[i] += S[i * SP + j] * v; }
; #pragma unroll
;       for (int i = 0; i < 16; ++i) red[(wave * 16 + i) * 64 + lane] = o[i];
;       __syncthreads();
; #pragma unroll
;       for (int rr = 0; rr < 2; ++rr) { const int i = wave * 2 + rr; float a = 0.f;
; #pragma unroll
;           for (int w = 0; w < 8; ++w) a += red[(w * 16 + i) * 64 + lane];
;           ((bf16*)(A.ws + WS_OB))[(size_t)(MP + s * 16 + i) * 1024 + h * 64 + lane] = (bf16)f2bf(a * linv[i]); } }
	v_mfma_f32_16x16x4_f32 v[4:7], v40, v60, v[4:7]
	v_mfma_f32_16x16x4_f32 v[8:11], v40, v61, v[8:11]
	v_mfma_f32_16x16x4_f32 v[12:15], v40, v62, v[12:15]
	v_mfma_f32_16x16x4_f32 v[16:19], v40, v63, v[16:19]
	ds_read_b32 v52, v93 offset:3328
	s_waitcnt vmcnt(7) lgkmcnt(1)
	v_mfma_f32_16x16x4_f32 v[4:7], v41, v64, v[4:7]
	v_mfma_f32_16x16x4_f32 v[8:11], v41, v65, v[8:11]
	v_mfma_f32_16x16x4_f32 v[12:15], v41, v66, v[12:15]
	v_mfma_f32_16x16x4_f32 v[16:19], v41, v67, v[16:19]
	ds_read_b32 v53, v93 offset:3456
	s_waitcnt vmcnt(6) lgkmcnt(1)
	v_mfma_f32_16x16x4_f32 v[4:7], v52, v68, v[4:7]
	v_mfma_f32_16x16x4_f32 v[8:11], v52, v69, v[8:11]
	v_mfma_f32_16x16x4_f32 v[12:15], v52, v70, v[12:15]
	v_mfma_f32_16x16x4_f32 v[16:19], v52, v71, v[16:19]
	ds_read_b32 v40, v93 offset:3584
	s_waitcnt vmcnt(5) lgkmcnt(1)
	v_mfma_f32_16x16x4_f32 v[4:7], v53, v72, v[4:7]
	v_mfma_f32_16x16x4_f32 v[8:11], v53, v73, v[8:11]
	v_mfma_f32_16x16x4_f32 v[12:15], v53, v74, v[12:15]
	v_mfma_f32_16x16x4_f32 v[16:19], v53, v75, v[16:19]
	ds_read_b32 v41, v93 offset:3712
	s_waitcnt vmcnt(4) lgkmcnt(1)
	v_mfma_f32_16x16x4_f32 v[4:7], v40, v76, v[4:7]
	v_mfma_f32_16x16x4_f32 v[8:11], v40, v77, v[8:11]
	v_mfma_f32_16x16x4_f32 v[12:15], v40, v78, v[12:15]
	v_mfma_f32_16x16x4_f32 v[16:19], v40, v79, v[16:19]
	ds_read_b32 v52, v93 offset:3840
	s_waitcnt vmcnt(3) lgkmcnt(1)
	v_mfma_f32_16x16x4_f32 v[4:7], v41, v80, v[4:7]
	v_mfma_f32_16x16x4_f32 v[8:11], v41, v81, v[8:11]
	v_mfma_f32_16x16x4_f32 v[12:15], v41, v82, v[12:15]
	v_mfma_f32_16x16x4_f32 v[16:19], v41, v83, v[16:19]
	ds_read_b32 v53, v93 offset:3968
	s_waitcnt vmcnt(2) lgkmcnt(1)
	v_mfma_f32_16x16x4_f32 v[4:7], v52, v84, v[4:7]
	v_mfma_f32_16x16x4_f32 v[8:11], v52, v85, v[8:11]
	v_mfma_f32_16x16x4_f32 v[12:15], v52, v86, v[12:15]
	v_mfma_f32_16x16x4_f32 v[16:19], v52, v87, v[16:19]
	ds_read_b32 v40, v93 offset:4096
	s_waitcnt vmcnt(1) lgkmcnt(1)
	v_mfma_f32_16x16x4_f32 v[4:7], v53, v88, v[4:7]
	v_mfma_f32_16x16x4_f32 v[8:11], v53, v89, v[8:11]
	v_mfma_f32_16x16x4_f32 v[12:15], v53, v90, v[12:15]
	v_mfma_f32_16x16x4_f32 v[16:19], v53, v91, v[16:19]
	s_cmp_lt_u32 s22, 4
	s_cbranch_scc0 .Lsfx_nonew
	s_waitcnt vmcnt(0) lgkmcnt(0)
	v_mfma_f32_16x16x4_f32 v[4:7], v40, v20, v[4:7]
	v_mfma_f32_16x16x4_f32 v[8:11], v40, v21, v[8:11]
	v_mfma_f32_16x16x4_f32 v[12:15], v40, v22, v[12:15]
	v_mfma_f32_16x16x4_f32 v[16:19], v40, v23, v[16:19]
.Lsfx_nonew:
	s_waitcnt vmcnt(0) lgkmcnt(0)
	v_readlane_b32 s6, v255, 18
	v_and_b32_e32 v40, 15, v0
	v_bfe_u32 v41, v0, 4, 2
	v_lshlrev_b32_e32 v40, 4, v40
	s_lshl_b32 s7, s22, 12
	v_lshl_or_b32 v40, v41, 10, v40
	s_add_i32 s7, s7, s6
	s_nop 7
	v_add_u32_e32 v40, s7, v40
	ds_write2_b32 v40, v4, v8 offset0:0 offset1:1
	ds_write2_b32 v40, v12, v16 offset0:2 offset1:3
	ds_write2_b32 v40, v5, v9 offset0:64 offset1:65
	ds_write2_b32 v40, v13, v17 offset0:66 offset1:67
	ds_write2_b32 v40, v6, v10 offset0:128 offset1:129
	ds_write2_b32 v40, v14, v18 offset0:130 offset1:131
	ds_write2_b32 v40, v7, v11 offset0:192 offset1:193
	ds_write2_b32 v40, v15, v19 offset0:194 offset1:195
	v_readlane_b32 s2, v255, 18
	s_lshl_b32 s28, s27, 1
	s_mov_b64 s[42:43], 0
	v_lshl_add_u32 v2, v0, 2, s2
	v_lshl_add_u32 v8, v55, 9, v2
	s_waitcnt lgkmcnt(0)
	s_barrier
	ds_read2st64_b32 v[4:5], v8 offset1:16
	ds_read2st64_b32 v[6:7], v8 offset0:32 offset1:48
	v_or_b32_e32 v12, 1, v54
	v_lshl_add_u64 v[0:1], v[0:1], 1, s[8:9]
	v_lshl_add_u32 v2, v12, 8, v2
	s_waitcnt lgkmcnt(1)
	v_add_f32_e32 v4, 0, v4
	v_add_f32_e32 v4, v4, v5
	s_waitcnt lgkmcnt(0)
	v_add_f32_e32 v6, v4, v6
	ds_read2st64_b32 v[4:5], v8 offset0:64 offset1:80
	v_add_f32_e32 v10, v6, v7
	ds_read2st64_b32 v[6:7], v8 offset0:96 offset1:112
	v_lshl_add_u32 v8, v54, 2, 0
	ds_read_b64 v[8:9], v8 offset:8320
	s_waitcnt lgkmcnt(2)
	v_add_f32_e32 v4, v10, v4
	v_add_f32_e32 v4, v4, v5
	s_waitcnt lgkmcnt(1)
	v_add_f32_e32 v4, v4, v6
	v_add_f32_e32 v4, v4, v7
	s_waitcnt lgkmcnt(0)
	v_mul_f32_e32 v4, v4, v8
	v_bfe_u32 v5, v4, 16, 1
	v_add3_u32 v8, v4, v5, s74
	v_add_u32_e32 v4, s4, v54
	v_ashrrev_i32_e32 v5, 31, v4
	v_lshl_add_u64 v[0:1], v[0:1], 0, s[28:29]
	ds_read2st64_b32 v[6:7], v2 offset1:16
	v_lshlrev_b64 v[4:5], 11, v[4:5]
	v_lshl_add_u64 v[4:5], v[0:1], 0, v[4:5]
	global_store_short_d16_hi v[4:5], v8, off
	ds_read2st64_b32 v[4:5], v2 offset0:32 offset1:48
	ds_read2st64_b32 v[10:11], v2 offset0:64 offset1:80
	s_waitcnt lgkmcnt(2)
	v_add_f32_e32 v6, 0, v6
	v_add_f32_e32 v8, v6, v7
	ds_read2st64_b32 v[6:7], v2 offset0:96 offset1:112
	s_waitcnt lgkmcnt(2)
	v_add_f32_e32 v2, v8, v4
	v_add_f32_e32 v2, v2, v5
	s_waitcnt lgkmcnt(1)
	v_add_f32_e32 v2, v2, v10
	v_add_f32_e32 v2, v2, v11
	s_waitcnt lgkmcnt(0)
	v_add_f32_e32 v2, v2, v6
	v_add_f32_e32 v2, v2, v7
	v_mul_f32_e32 v2, v2, v9
	v_bfe_u32 v4, v2, 16, 1
	v_add3_u32 v2, v2, v4, s74
	v_add_u32_e32 v4, s4, v12
	v_ashrrev_i32_e32 v5, 31, v4
	v_lshlrev_b64 v[4:5], 11, v[4:5]
	v_lshl_add_u64 v[0:1], v[0:1], 0, v[4:5]
	global_store_short_d16_hi v[0:1], v2, off
	s_barrier
